# w_uq conversion also assigned from the opposite end (phase-1 idle workgroups now 5 item rounds instead of 6-7)
# speedup vs baseline: 1.0044x; 1.0044x over previous
; #define LAS __attribute__((address_space(3)))
; __device__ __forceinline__ void conv_matrix(const float* W, int K, int N, const float* gain, bf16_t* WT, int Kd, int mode, int row_off, LAS float* scr, int lane, int gw, int NGW) {
;     const int nblk = N / 32, items = nblk * (K / 64);
;     for (int it = gw; it < items; it += NGW) {
;         const int kb = it / nblk, nb = it % nblk, k0 = 64 * kb, n0 = 32 * nb;
;         float wv[32];
; #pragma unroll
;         for (int i = 0; i < 32; ++i) wv[i] = W[(size_t)(k0 + 2 * i + (lane >> 5)) * N + n0 + (lane & 31)];
.Lskip_c3:
.LBB0_115:
	s_sub_i32 s22, s8, s4
	s_add_i32 s22, s22, -1
	s_cmpk_gt_i32 s22, 0x17f
	s_cbranch_scc1 .LBB0_120
	v_readlane_b32 s9, v254, 13
	v_lshlrev_b32_e32 v6, 2, v54
	v_and_b32_e32 v6, 0x7c, v6
	v_mov_b32_e32 v2, s9
	v_readlane_b32 s9, v254, 14
	v_mov_b32_e32 v7, v0
	v_add_u32_e32 v8, s5, v6
	v_mov_b32_e32 v4, s9
	ds_read_b64 v[2:3], v2
	ds_read_b64 v[4:5], v4
	v_lshrrev_b32_e32 v44, 3, v1
	v_lshrrev_b32_e32 v35, 5, v1
	v_lshlrev_b32_e32 v10, 2, v44
	s_mov_b64 s[16:17], 0xcd00000
	s_waitcnt lgkmcnt(0)
	v_lshl_add_u64 v[4:5], v[4:5], 0, v[6:7]
	v_lshlrev_b32_e32 v6, 3, v1
	v_and_b32_e32 v6, 56, v6
	v_mul_u32_u24_e32 v9, 0x84, v6
	v_lshlrev_b32_e32 v6, 1, v6
	v_lshl_add_u64 v[6:7], s[0:1], 0, v[6:7]
	v_add3_u32 v45, s5, v9, v10
	v_mul_u32_u24_e32 v9, 0x84, v35
	v_cmp_ne_u64_e64 s[40:41], 0, v[2:3]
	v_lshl_add_u64 v[6:7], v[6:7], 0, s[16:17]
	s_lshl_b32 s9, s22, 5
	s_lshl_b32 s12, s8, 5
	v_add_u32_e32 v46, v8, v9
	s_cmp_lg_u32 s58, 1
	s_cbranch_scc1 .LBB0_120
	s_branch .LBB0_118
